# merge phase EpiGated<1> epilogue rewritten by hand: G/MB loads batched with counted vmcnt (was 32 serialized round trips)
# speedup vs baseline: 1.0228x; 1.0038x over previous
.LBB0_211:
	s_lshl_b32 s14, s64, 8
	v_mbcnt_lo_u32_b32 v96, -1, 0
	v_mbcnt_hi_u32_b32 v96, -1, v96
	s_add_i32 s14, s14, s71
	v_and_or_b32 v134, v96, 15, s14
	s_lshl_b32 s14, s62, 8
	v_lshrrev_b32_e32 v96, 1, v96
	v_and_or_b32 v96, v96, 24, s14
	v_or_b32_e32 v132, s91, v96
	v_ashrrev_i32_e32 v135, 31, v134
	v_ashrrev_i32_e32 v133, 31, v132
	v_lshlrev_b64 v[130:131], 10, v[134:135]
	v_lshl_add_u64 v[130:131], v[130:131], 0, v[132:133]
	v_lshl_add_u64 v[164:165], s[88:89], 0, v[130:131]
	v_lshl_add_u64 v[204:205], v[130:131], 1, s[94:95]
	s_mov_b32 s101, 0
	global_load_dwordx2 v[220:221], v[164:165], off
	global_load_dwordx2 v[222:223], v[164:165], off offset:128
	s_mov_b32 s100, 0x4000
	v_lshl_add_u64 v[164:165], s[100:101], 0, v[164:165]
	global_load_dwordx2 v[224:225], v[164:165], off
	global_load_dwordx2 v[226:227], v[164:165], off offset:128
	s_mov_b32 s100, 0x4000
	v_lshl_add_u64 v[164:165], s[100:101], 0, v[164:165]
	global_load_dwordx2 v[228:229], v[164:165], off
	global_load_dwordx2 v[230:231], v[164:165], off offset:128
	s_mov_b32 s100, 0x4000
	v_lshl_add_u64 v[164:165], s[100:101], 0, v[164:165]
	global_load_dwordx2 v[232:233], v[164:165], off
	global_load_dwordx2 v[234:235], v[164:165], off offset:128
	s_mov_b32 s100, 0x14000
	v_lshl_add_u64 v[164:165], s[100:101], 0, v[164:165]
	global_load_dwordx2 v[236:237], v[164:165], off
	global_load_dwordx2 v[238:239], v[164:165], off offset:128
	s_mov_b32 s100, 0x4000
	v_lshl_add_u64 v[164:165], s[100:101], 0, v[164:165]
	global_load_dwordx2 v[240:241], v[164:165], off
	global_load_dwordx2 v[242:243], v[164:165], off offset:128
	s_mov_b32 s100, 0x4000
	v_lshl_add_u64 v[164:165], s[100:101], 0, v[164:165]
	global_load_dwordx2 v[244:245], v[164:165], off
	global_load_dwordx2 v[246:247], v[164:165], off offset:128
	s_mov_b32 s100, 0x4000
	v_lshl_add_u64 v[164:165], s[100:101], 0, v[164:165]
	global_load_dwordx2 v[248:249], v[164:165], off
	global_load_dwordx2 v[250:251], v[164:165], off offset:128
	s_mov_b32 s100, 0x8000
	v_lshl_add_u64 v[206:207], s[100:101], 0, v[204:205]
	s_mov_b32 s100, 0x8000
	v_lshl_add_u64 v[208:209], s[100:101], 0, v[206:207]
	s_mov_b32 s100, 0x8000
	v_lshl_add_u64 v[210:211], s[100:101], 0, v[208:209]
	s_mov_b32 s100, 0x28000
	v_lshl_add_u64 v[212:213], s[100:101], 0, v[210:211]
	s_mov_b32 s100, 0x8000
	v_lshl_add_u64 v[158:159], s[100:101], 0, v[212:213]
	s_mov_b32 s100, 0x8000
	v_lshl_add_u64 v[160:161], s[100:101], 0, v[158:159]
	s_mov_b32 s100, 0x8000
	v_lshl_add_u64 v[162:163], s[100:101], 0, v[160:161]
	global_load_dwordx4 v[172:175], v[204:205], off
	global_load_dwordx4 v[176:179], v[204:205], off offset:256
	global_load_dwordx4 v[180:183], v[206:207], off
	global_load_dwordx4 v[184:187], v[206:207], off offset:256
	global_load_dwordx4 v[188:191], v[208:209], off
	global_load_dwordx4 v[192:195], v[208:209], off offset:256
	global_load_dwordx4 v[196:199], v[210:211], off
	global_load_dwordx4 v[200:203], v[210:211], off offset:256
	s_waitcnt vmcnt(7)
	v_cvt_f32_ubyte0_e32 v130, v220
	v_cvt_f32_ubyte1_e32 v131, v220
	v_cvt_f32_ubyte2_e32 v132, v220
	v_cvt_f32_ubyte3_e32 v133, v220
	v_cvt_f32_ubyte0_e32 v134, v221
	v_cvt_f32_ubyte1_e32 v135, v221
	v_cvt_f32_ubyte2_e32 v136, v221
	v_cvt_f32_ubyte3_e32 v137, v221
	v_lshlrev_b32_e32 v138, 16, v172
	v_and_b32_e32 v139, 0xffff0000, v172
	v_lshlrev_b32_e32 v140, 16, v173
	v_and_b32_e32 v141, 0xffff0000, v173
	v_lshlrev_b32_e32 v142, 16, v174
	v_and_b32_e32 v143, 0xffff0000, v174
	v_lshlrev_b32_e32 v144, 16, v175
	v_and_b32_e32 v145, 0xffff0000, v175
	v_pk_mul_f32 v[130:131], v[130:131], s[34:35] op_sel_hi:[1,0]
	v_pk_mul_f32 v[132:133], v[132:133], s[34:35] op_sel_hi:[1,0]
	v_pk_mul_f32 v[134:135], v[134:135], s[34:35] op_sel_hi:[1,0]
	v_pk_mul_f32 v[136:137], v[136:137], s[34:35] op_sel_hi:[1,0]
	v_pk_fma_f32 v[130:131], v[126:127], v[130:131], v[138:139]
	v_pk_fma_f32 v[132:133], v[128:129], v[132:133], v[140:141]
	v_pk_fma_f32 v[134:135], v[122:123], v[134:135], v[142:143]
	v_pk_fma_f32 v[136:137], v[124:125], v[136:137], v[144:145]
	v_cvt_pk_bf16_f32 v150, v130, v131
	v_cvt_pk_bf16_f32 v151, v132, v133
	v_cvt_pk_bf16_f32 v152, v134, v135
	v_cvt_pk_bf16_f32 v153, v136, v137
	global_store_dwordx4 v[204:205], v[150:153], off
	global_load_dwordx4 v[172:175], v[212:213], off
	s_waitcnt vmcnt(8)
	v_cvt_f32_ubyte0_e32 v130, v222
	v_cvt_f32_ubyte1_e32 v131, v222
	v_cvt_f32_ubyte2_e32 v132, v222
	v_cvt_f32_ubyte3_e32 v133, v222
	v_cvt_f32_ubyte0_e32 v134, v223
	v_cvt_f32_ubyte1_e32 v135, v223
	v_cvt_f32_ubyte2_e32 v136, v223
	v_cvt_f32_ubyte3_e32 v137, v223
	v_lshlrev_b32_e32 v138, 16, v176
	v_and_b32_e32 v139, 0xffff0000, v176
	v_lshlrev_b32_e32 v140, 16, v177
	v_and_b32_e32 v141, 0xffff0000, v177
	v_lshlrev_b32_e32 v142, 16, v178
	v_and_b32_e32 v143, 0xffff0000, v178
	v_lshlrev_b32_e32 v144, 16, v179
	v_and_b32_e32 v145, 0xffff0000, v179
	v_pk_mul_f32 v[130:131], v[130:131], s[34:35] op_sel_hi:[1,0]
	v_pk_mul_f32 v[132:133], v[132:133], s[34:35] op_sel_hi:[1,0]
	v_pk_mul_f32 v[134:135], v[134:135], s[34:35] op_sel_hi:[1,0]
	v_pk_mul_f32 v[136:137], v[136:137], s[34:35] op_sel_hi:[1,0]
	v_pk_fma_f32 v[130:131], v[118:119], v[130:131], v[138:139]
	v_pk_fma_f32 v[132:133], v[120:121], v[132:133], v[140:141]
	v_pk_fma_f32 v[134:135], v[114:115], v[134:135], v[142:143]
	v_pk_fma_f32 v[136:137], v[116:117], v[136:137], v[144:145]
	v_cvt_pk_bf16_f32 v154, v130, v131
	v_cvt_pk_bf16_f32 v155, v132, v133
	v_cvt_pk_bf16_f32 v156, v134, v135
	v_cvt_pk_bf16_f32 v157, v136, v137
	global_store_dwordx4 v[204:205], v[154:157], off offset:256
	global_load_dwordx4 v[176:179], v[212:213], off offset:256
	s_waitcnt vmcnt(9)
	v_cvt_f32_ubyte0_e32 v130, v224
	v_cvt_f32_ubyte1_e32 v131, v224
	v_cvt_f32_ubyte2_e32 v132, v224
	v_cvt_f32_ubyte3_e32 v133, v224
	v_cvt_f32_ubyte0_e32 v134, v225
	v_cvt_f32_ubyte1_e32 v135, v225
	v_cvt_f32_ubyte2_e32 v136, v225
	v_cvt_f32_ubyte3_e32 v137, v225
	v_lshlrev_b32_e32 v138, 16, v180
	v_and_b32_e32 v139, 0xffff0000, v180
	v_lshlrev_b32_e32 v140, 16, v181
	v_and_b32_e32 v141, 0xffff0000, v181
	v_lshlrev_b32_e32 v142, 16, v182
	v_and_b32_e32 v143, 0xffff0000, v182
	v_lshlrev_b32_e32 v144, 16, v183
	v_and_b32_e32 v145, 0xffff0000, v183
	v_pk_mul_f32 v[130:131], v[130:131], s[34:35] op_sel_hi:[1,0]
	v_pk_mul_f32 v[132:133], v[132:133], s[34:35] op_sel_hi:[1,0]
	v_pk_mul_f32 v[134:135], v[134:135], s[34:35] op_sel_hi:[1,0]
	v_pk_mul_f32 v[136:137], v[136:137], s[34:35] op_sel_hi:[1,0]
	v_pk_fma_f32 v[130:131], v[110:111], v[130:131], v[138:139]
	v_pk_fma_f32 v[132:133], v[112:113], v[132:133], v[140:141]
	v_pk_fma_f32 v[134:135], v[106:107], v[134:135], v[142:143]
	v_pk_fma_f32 v[136:137], v[108:109], v[136:137], v[144:145]
	v_cvt_pk_bf16_f32 v150, v130, v131
	v_cvt_pk_bf16_f32 v151, v132, v133
	v_cvt_pk_bf16_f32 v152, v134, v135
	v_cvt_pk_bf16_f32 v153, v136, v137
	global_store_dwordx4 v[206:207], v[150:153], off
	global_load_dwordx4 v[180:183], v[158:159], off
	s_waitcnt vmcnt(10)
	v_cvt_f32_ubyte0_e32 v130, v226
	v_cvt_f32_ubyte1_e32 v131, v226
	v_cvt_f32_ubyte2_e32 v132, v226
	v_cvt_f32_ubyte3_e32 v133, v226
	v_cvt_f32_ubyte0_e32 v134, v227
	v_cvt_f32_ubyte1_e32 v135, v227
	v_cvt_f32_ubyte2_e32 v136, v227
	v_cvt_f32_ubyte3_e32 v137, v227
	v_lshlrev_b32_e32 v138, 16, v184
	v_and_b32_e32 v139, 0xffff0000, v184
	v_lshlrev_b32_e32 v140, 16, v185
	v_and_b32_e32 v141, 0xffff0000, v185
	v_lshlrev_b32_e32 v142, 16, v186
	v_and_b32_e32 v143, 0xffff0000, v186
	v_lshlrev_b32_e32 v144, 16, v187
	v_and_b32_e32 v145, 0xffff0000, v187
	v_pk_mul_f32 v[130:131], v[130:131], s[34:35] op_sel_hi:[1,0]
	v_pk_mul_f32 v[132:133], v[132:133], s[34:35] op_sel_hi:[1,0]
	v_pk_mul_f32 v[134:135], v[134:135], s[34:35] op_sel_hi:[1,0]
	v_pk_mul_f32 v[136:137], v[136:137], s[34:35] op_sel_hi:[1,0]
	v_pk_fma_f32 v[130:131], v[102:103], v[130:131], v[138:139]
	v_pk_fma_f32 v[132:133], v[104:105], v[132:133], v[140:141]
	v_pk_fma_f32 v[134:135], v[98:99], v[134:135], v[142:143]
	v_pk_fma_f32 v[136:137], v[100:101], v[136:137], v[144:145]
	v_cvt_pk_bf16_f32 v154, v130, v131
	v_cvt_pk_bf16_f32 v155, v132, v133
	v_cvt_pk_bf16_f32 v156, v134, v135
	v_cvt_pk_bf16_f32 v157, v136, v137
	global_store_dwordx4 v[206:207], v[154:157], off offset:256
	global_load_dwordx4 v[184:187], v[158:159], off offset:256
	s_waitcnt vmcnt(11)
	v_cvt_f32_ubyte0_e32 v130, v228
	v_cvt_f32_ubyte1_e32 v131, v228
	v_cvt_f32_ubyte2_e32 v132, v228
	v_cvt_f32_ubyte3_e32 v133, v228
	v_cvt_f32_ubyte0_e32 v134, v229
	v_cvt_f32_ubyte1_e32 v135, v229
	v_cvt_f32_ubyte2_e32 v136, v229
	v_cvt_f32_ubyte3_e32 v137, v229
	v_lshlrev_b32_e32 v138, 16, v188
	v_and_b32_e32 v139, 0xffff0000, v188
	v_lshlrev_b32_e32 v140, 16, v189
	v_and_b32_e32 v141, 0xffff0000, v189
	v_lshlrev_b32_e32 v142, 16, v190
	v_and_b32_e32 v143, 0xffff0000, v190
	v_lshlrev_b32_e32 v144, 16, v191
	v_and_b32_e32 v145, 0xffff0000, v191
	v_pk_mul_f32 v[130:131], v[130:131], s[34:35] op_sel_hi:[1,0]
	v_pk_mul_f32 v[132:133], v[132:133], s[34:35] op_sel_hi:[1,0]
	v_pk_mul_f32 v[134:135], v[134:135], s[34:35] op_sel_hi:[1,0]
	v_pk_mul_f32 v[136:137], v[136:137], s[34:35] op_sel_hi:[1,0]
	v_pk_fma_f32 v[130:131], v[92:93], v[130:131], v[138:139]
	v_pk_fma_f32 v[132:133], v[94:95], v[132:133], v[140:141]
	v_pk_fma_f32 v[134:135], v[88:89], v[134:135], v[142:143]
	v_pk_fma_f32 v[136:137], v[90:91], v[136:137], v[144:145]
	v_cvt_pk_bf16_f32 v150, v130, v131
	v_cvt_pk_bf16_f32 v151, v132, v133
	v_cvt_pk_bf16_f32 v152, v134, v135
	v_cvt_pk_bf16_f32 v153, v136, v137
	global_store_dwordx4 v[208:209], v[150:153], off
	global_load_dwordx4 v[188:191], v[160:161], off
	s_waitcnt vmcnt(12)
	v_cvt_f32_ubyte0_e32 v130, v230
	v_cvt_f32_ubyte1_e32 v131, v230
	v_cvt_f32_ubyte2_e32 v132, v230
	v_cvt_f32_ubyte3_e32 v133, v230
	v_cvt_f32_ubyte0_e32 v134, v231
	v_cvt_f32_ubyte1_e32 v135, v231
	v_cvt_f32_ubyte2_e32 v136, v231
	v_cvt_f32_ubyte3_e32 v137, v231
	v_lshlrev_b32_e32 v138, 16, v192
	v_and_b32_e32 v139, 0xffff0000, v192
	v_lshlrev_b32_e32 v140, 16, v193
	v_and_b32_e32 v141, 0xffff0000, v193
	v_lshlrev_b32_e32 v142, 16, v194
	v_and_b32_e32 v143, 0xffff0000, v194
	v_lshlrev_b32_e32 v144, 16, v195
	v_and_b32_e32 v145, 0xffff0000, v195
	v_pk_mul_f32 v[130:131], v[130:131], s[34:35] op_sel_hi:[1,0]
	v_pk_mul_f32 v[132:133], v[132:133], s[34:35] op_sel_hi:[1,0]
	v_pk_mul_f32 v[134:135], v[134:135], s[34:35] op_sel_hi:[1,0]
	v_pk_mul_f32 v[136:137], v[136:137], s[34:35] op_sel_hi:[1,0]
	v_pk_fma_f32 v[130:131], v[84:85], v[130:131], v[138:139]
	v_pk_fma_f32 v[132:133], v[86:87], v[132:133], v[140:141]
	v_pk_fma_f32 v[134:135], v[80:81], v[134:135], v[142:143]
	v_pk_fma_f32 v[136:137], v[82:83], v[136:137], v[144:145]
	v_cvt_pk_bf16_f32 v154, v130, v131
	v_cvt_pk_bf16_f32 v155, v132, v133
	v_cvt_pk_bf16_f32 v156, v134, v135
	v_cvt_pk_bf16_f32 v157, v136, v137
	global_store_dwordx4 v[208:209], v[154:157], off offset:256
	global_load_dwordx4 v[192:195], v[160:161], off offset:256
	s_waitcnt vmcnt(13)
	v_cvt_f32_ubyte0_e32 v130, v232
	v_cvt_f32_ubyte1_e32 v131, v232
	v_cvt_f32_ubyte2_e32 v132, v232
	v_cvt_f32_ubyte3_e32 v133, v232
	v_cvt_f32_ubyte0_e32 v134, v233
	v_cvt_f32_ubyte1_e32 v135, v233
	v_cvt_f32_ubyte2_e32 v136, v233
	v_cvt_f32_ubyte3_e32 v137, v233
	v_lshlrev_b32_e32 v138, 16, v196
	v_and_b32_e32 v139, 0xffff0000, v196
	v_lshlrev_b32_e32 v140, 16, v197
	v_and_b32_e32 v141, 0xffff0000, v197
	v_lshlrev_b32_e32 v142, 16, v198
	v_and_b32_e32 v143, 0xffff0000, v198
	v_lshlrev_b32_e32 v144, 16, v199
	v_and_b32_e32 v145, 0xffff0000, v199
	v_pk_mul_f32 v[130:131], v[130:131], s[34:35] op_sel_hi:[1,0]
	v_pk_mul_f32 v[132:133], v[132:133], s[34:35] op_sel_hi:[1,0]
	v_pk_mul_f32 v[134:135], v[134:135], s[34:35] op_sel_hi:[1,0]
	v_pk_mul_f32 v[136:137], v[136:137], s[34:35] op_sel_hi:[1,0]
	v_pk_fma_f32 v[130:131], v[76:77], v[130:131], v[138:139]
	v_pk_fma_f32 v[132:133], v[78:79], v[132:133], v[140:141]
	v_pk_fma_f32 v[134:135], v[72:73], v[134:135], v[142:143]
	v_pk_fma_f32 v[136:137], v[74:75], v[136:137], v[144:145]
	v_cvt_pk_bf16_f32 v150, v130, v131
	v_cvt_pk_bf16_f32 v151, v132, v133
	v_cvt_pk_bf16_f32 v152, v134, v135
	v_cvt_pk_bf16_f32 v153, v136, v137
	global_store_dwordx4 v[210:211], v[150:153], off
	global_load_dwordx4 v[196:199], v[162:163], off
	s_waitcnt vmcnt(14)
	v_cvt_f32_ubyte0_e32 v130, v234
	v_cvt_f32_ubyte1_e32 v131, v234
	v_cvt_f32_ubyte2_e32 v132, v234
	v_cvt_f32_ubyte3_e32 v133, v234
	v_cvt_f32_ubyte0_e32 v134, v235
	v_cvt_f32_ubyte1_e32 v135, v235
	v_cvt_f32_ubyte2_e32 v136, v235
	v_cvt_f32_ubyte3_e32 v137, v235
	v_lshlrev_b32_e32 v138, 16, v200
	v_and_b32_e32 v139, 0xffff0000, v200
	v_lshlrev_b32_e32 v140, 16, v201
	v_and_b32_e32 v141, 0xffff0000, v201
	v_lshlrev_b32_e32 v142, 16, v202
	v_and_b32_e32 v143, 0xffff0000, v202
	v_lshlrev_b32_e32 v144, 16, v203
	v_and_b32_e32 v145, 0xffff0000, v203
	v_pk_mul_f32 v[130:131], v[130:131], s[34:35] op_sel_hi:[1,0]
	v_pk_mul_f32 v[132:133], v[132:133], s[34:35] op_sel_hi:[1,0]
	v_pk_mul_f32 v[134:135], v[134:135], s[34:35] op_sel_hi:[1,0]
	v_pk_mul_f32 v[136:137], v[136:137], s[34:35] op_sel_hi:[1,0]
	v_pk_fma_f32 v[130:131], v[68:69], v[130:131], v[138:139]
	v_pk_fma_f32 v[132:133], v[70:71], v[132:133], v[140:141]
	v_pk_fma_f32 v[134:135], v[64:65], v[134:135], v[142:143]
	v_pk_fma_f32 v[136:137], v[66:67], v[136:137], v[144:145]
	v_cvt_pk_bf16_f32 v154, v130, v131
	v_cvt_pk_bf16_f32 v155, v132, v133
	v_cvt_pk_bf16_f32 v156, v134, v135
	v_cvt_pk_bf16_f32 v157, v136, v137
	global_store_dwordx4 v[210:211], v[154:157], off offset:256
	global_load_dwordx4 v[200:203], v[162:163], off offset:256
	s_waitcnt vmcnt(14)
	v_cvt_f32_ubyte0_e32 v130, v236
	v_cvt_f32_ubyte1_e32 v131, v236
	v_cvt_f32_ubyte2_e32 v132, v236
	v_cvt_f32_ubyte3_e32 v133, v236
	v_cvt_f32_ubyte0_e32 v134, v237
	v_cvt_f32_ubyte1_e32 v135, v237
	v_cvt_f32_ubyte2_e32 v136, v237
	v_cvt_f32_ubyte3_e32 v137, v237
	v_lshlrev_b32_e32 v138, 16, v172
	v_and_b32_e32 v139, 0xffff0000, v172
	v_lshlrev_b32_e32 v140, 16, v173
	v_and_b32_e32 v141, 0xffff0000, v173
	v_lshlrev_b32_e32 v142, 16, v174
	v_and_b32_e32 v143, 0xffff0000, v174
	v_lshlrev_b32_e32 v144, 16, v175
	v_and_b32_e32 v145, 0xffff0000, v175
	v_pk_mul_f32 v[130:131], v[130:131], s[34:35] op_sel_hi:[1,0]
	v_pk_mul_f32 v[132:133], v[132:133], s[34:35] op_sel_hi:[1,0]
	v_pk_mul_f32 v[134:135], v[134:135], s[34:35] op_sel_hi:[1,0]
	v_pk_mul_f32 v[136:137], v[136:137], s[34:35] op_sel_hi:[1,0]
	v_pk_fma_f32 v[130:131], v[60:61], v[130:131], v[138:139]
	v_pk_fma_f32 v[132:133], v[62:63], v[132:133], v[140:141]
	v_pk_fma_f32 v[134:135], v[56:57], v[134:135], v[142:143]
	v_pk_fma_f32 v[136:137], v[58:59], v[136:137], v[144:145]
	v_cvt_pk_bf16_f32 v150, v130, v131
	v_cvt_pk_bf16_f32 v151, v132, v133
	v_cvt_pk_bf16_f32 v152, v134, v135
	v_cvt_pk_bf16_f32 v153, v136, v137
	global_store_dwordx4 v[212:213], v[150:153], off
	s_waitcnt vmcnt(13)
	v_cvt_f32_ubyte0_e32 v130, v238
	v_cvt_f32_ubyte1_e32 v131, v238
	v_cvt_f32_ubyte2_e32 v132, v238
	v_cvt_f32_ubyte3_e32 v133, v238
	v_cvt_f32_ubyte0_e32 v134, v239
	v_cvt_f32_ubyte1_e32 v135, v239
	v_cvt_f32_ubyte2_e32 v136, v239
	v_cvt_f32_ubyte3_e32 v137, v239
	v_lshlrev_b32_e32 v138, 16, v176
	v_and_b32_e32 v139, 0xffff0000, v176
	v_lshlrev_b32_e32 v140, 16, v177
	v_and_b32_e32 v141, 0xffff0000, v177
	v_lshlrev_b32_e32 v142, 16, v178
	v_and_b32_e32 v143, 0xffff0000, v178
	v_lshlrev_b32_e32 v144, 16, v179
	v_and_b32_e32 v145, 0xffff0000, v179
	v_pk_mul_f32 v[130:131], v[130:131], s[34:35] op_sel_hi:[1,0]
	v_pk_mul_f32 v[132:133], v[132:133], s[34:35] op_sel_hi:[1,0]
	v_pk_mul_f32 v[134:135], v[134:135], s[34:35] op_sel_hi:[1,0]
	v_pk_mul_f32 v[136:137], v[136:137], s[34:35] op_sel_hi:[1,0]
	v_pk_fma_f32 v[130:131], v[52:53], v[130:131], v[138:139]
	v_pk_fma_f32 v[132:133], v[54:55], v[132:133], v[140:141]
	v_pk_fma_f32 v[134:135], v[48:49], v[134:135], v[142:143]
	v_pk_fma_f32 v[136:137], v[50:51], v[136:137], v[144:145]
	v_cvt_pk_bf16_f32 v154, v130, v131
	v_cvt_pk_bf16_f32 v155, v132, v133
	v_cvt_pk_bf16_f32 v156, v134, v135
	v_cvt_pk_bf16_f32 v157, v136, v137
	global_store_dwordx4 v[212:213], v[154:157], off offset:256
	s_waitcnt vmcnt(12)
	v_cvt_f32_ubyte0_e32 v130, v240
	v_cvt_f32_ubyte1_e32 v131, v240
	v_cvt_f32_ubyte2_e32 v132, v240
	v_cvt_f32_ubyte3_e32 v133, v240
	v_cvt_f32_ubyte0_e32 v134, v241
	v_cvt_f32_ubyte1_e32 v135, v241
	v_cvt_f32_ubyte2_e32 v136, v241
	v_cvt_f32_ubyte3_e32 v137, v241
	v_lshlrev_b32_e32 v138, 16, v180
	v_and_b32_e32 v139, 0xffff0000, v180
	v_lshlrev_b32_e32 v140, 16, v181
	v_and_b32_e32 v141, 0xffff0000, v181
	v_lshlrev_b32_e32 v142, 16, v182
	v_and_b32_e32 v143, 0xffff0000, v182
	v_lshlrev_b32_e32 v144, 16, v183
	v_and_b32_e32 v145, 0xffff0000, v183
	v_pk_mul_f32 v[130:131], v[130:131], s[34:35] op_sel_hi:[1,0]
	v_pk_mul_f32 v[132:133], v[132:133], s[34:35] op_sel_hi:[1,0]
	v_pk_mul_f32 v[134:135], v[134:135], s[34:35] op_sel_hi:[1,0]
	v_pk_mul_f32 v[136:137], v[136:137], s[34:35] op_sel_hi:[1,0]
	v_pk_fma_f32 v[130:131], v[44:45], v[130:131], v[138:139]
	v_pk_fma_f32 v[132:133], v[46:47], v[132:133], v[140:141]
	v_pk_fma_f32 v[134:135], v[40:41], v[134:135], v[142:143]
	v_pk_fma_f32 v[136:137], v[42:43], v[136:137], v[144:145]
	v_cvt_pk_bf16_f32 v150, v130, v131
	v_cvt_pk_bf16_f32 v151, v132, v133
	v_cvt_pk_bf16_f32 v152, v134, v135
	v_cvt_pk_bf16_f32 v153, v136, v137
	global_store_dwordx4 v[158:159], v[150:153], off
	s_waitcnt vmcnt(11)
	v_cvt_f32_ubyte0_e32 v130, v242
	v_cvt_f32_ubyte1_e32 v131, v242
	v_cvt_f32_ubyte2_e32 v132, v242
	v_cvt_f32_ubyte3_e32 v133, v242
	v_cvt_f32_ubyte0_e32 v134, v243
	v_cvt_f32_ubyte1_e32 v135, v243
	v_cvt_f32_ubyte2_e32 v136, v243
	v_cvt_f32_ubyte3_e32 v137, v243
	v_lshlrev_b32_e32 v138, 16, v184
	v_and_b32_e32 v139, 0xffff0000, v184
	v_lshlrev_b32_e32 v140, 16, v185
	v_and_b32_e32 v141, 0xffff0000, v185
	v_lshlrev_b32_e32 v142, 16, v186
	v_and_b32_e32 v143, 0xffff0000, v186
	v_lshlrev_b32_e32 v144, 16, v187
	v_and_b32_e32 v145, 0xffff0000, v187
	v_pk_mul_f32 v[130:131], v[130:131], s[34:35] op_sel_hi:[1,0]
	v_pk_mul_f32 v[132:133], v[132:133], s[34:35] op_sel_hi:[1,0]
	v_pk_mul_f32 v[134:135], v[134:135], s[34:35] op_sel_hi:[1,0]
	v_pk_mul_f32 v[136:137], v[136:137], s[34:35] op_sel_hi:[1,0]
	v_pk_fma_f32 v[130:131], v[36:37], v[130:131], v[138:139]
	v_pk_fma_f32 v[132:133], v[38:39], v[132:133], v[140:141]
	v_pk_fma_f32 v[134:135], v[32:33], v[134:135], v[142:143]
	v_pk_fma_f32 v[136:137], v[34:35], v[136:137], v[144:145]
	v_cvt_pk_bf16_f32 v154, v130, v131
	v_cvt_pk_bf16_f32 v155, v132, v133
	v_cvt_pk_bf16_f32 v156, v134, v135
	v_cvt_pk_bf16_f32 v157, v136, v137
	global_store_dwordx4 v[158:159], v[154:157], off offset:256
	s_waitcnt vmcnt(10)
	v_cvt_f32_ubyte0_e32 v130, v244
	v_cvt_f32_ubyte1_e32 v131, v244
	v_cvt_f32_ubyte2_e32 v132, v244
	v_cvt_f32_ubyte3_e32 v133, v244
	v_cvt_f32_ubyte0_e32 v134, v245
	v_cvt_f32_ubyte1_e32 v135, v245
	v_cvt_f32_ubyte2_e32 v136, v245
	v_cvt_f32_ubyte3_e32 v137, v245
	v_lshlrev_b32_e32 v138, 16, v188
	v_and_b32_e32 v139, 0xffff0000, v188
	v_lshlrev_b32_e32 v140, 16, v189
	v_and_b32_e32 v141, 0xffff0000, v189
	v_lshlrev_b32_e32 v142, 16, v190
	v_and_b32_e32 v143, 0xffff0000, v190
	v_lshlrev_b32_e32 v144, 16, v191
	v_and_b32_e32 v145, 0xffff0000, v191
	v_pk_mul_f32 v[130:131], v[130:131], s[34:35] op_sel_hi:[1,0]
	v_pk_mul_f32 v[132:133], v[132:133], s[34:35] op_sel_hi:[1,0]
	v_pk_mul_f32 v[134:135], v[134:135], s[34:35] op_sel_hi:[1,0]
	v_pk_mul_f32 v[136:137], v[136:137], s[34:35] op_sel_hi:[1,0]
	v_pk_fma_f32 v[130:131], v[28:29], v[130:131], v[138:139]
	v_pk_fma_f32 v[132:133], v[30:31], v[132:133], v[140:141]
	v_pk_fma_f32 v[134:135], v[24:25], v[134:135], v[142:143]
	v_pk_fma_f32 v[136:137], v[26:27], v[136:137], v[144:145]
	v_cvt_pk_bf16_f32 v150, v130, v131
	v_cvt_pk_bf16_f32 v151, v132, v133
	v_cvt_pk_bf16_f32 v152, v134, v135
	v_cvt_pk_bf16_f32 v153, v136, v137
	global_store_dwordx4 v[160:161], v[150:153], off
	s_waitcnt vmcnt(9)
	v_cvt_f32_ubyte0_e32 v130, v246
	v_cvt_f32_ubyte1_e32 v131, v246
	v_cvt_f32_ubyte2_e32 v132, v246
	v_cvt_f32_ubyte3_e32 v133, v246
	v_cvt_f32_ubyte0_e32 v134, v247
	v_cvt_f32_ubyte1_e32 v135, v247
	v_cvt_f32_ubyte2_e32 v136, v247
	v_cvt_f32_ubyte3_e32 v137, v247
	v_lshlrev_b32_e32 v138, 16, v192
	v_and_b32_e32 v139, 0xffff0000, v192
	v_lshlrev_b32_e32 v140, 16, v193
	v_and_b32_e32 v141, 0xffff0000, v193
	v_lshlrev_b32_e32 v142, 16, v194
	v_and_b32_e32 v143, 0xffff0000, v194
	v_lshlrev_b32_e32 v144, 16, v195
	v_and_b32_e32 v145, 0xffff0000, v195
	v_pk_mul_f32 v[130:131], v[130:131], s[34:35] op_sel_hi:[1,0]
	v_pk_mul_f32 v[132:133], v[132:133], s[34:35] op_sel_hi:[1,0]
	v_pk_mul_f32 v[134:135], v[134:135], s[34:35] op_sel_hi:[1,0]
	v_pk_mul_f32 v[136:137], v[136:137], s[34:35] op_sel_hi:[1,0]
	v_pk_fma_f32 v[130:131], v[20:21], v[130:131], v[138:139]
	v_pk_fma_f32 v[132:133], v[22:23], v[132:133], v[140:141]
	v_pk_fma_f32 v[134:135], v[16:17], v[134:135], v[142:143]
	v_pk_fma_f32 v[136:137], v[18:19], v[136:137], v[144:145]
	v_cvt_pk_bf16_f32 v154, v130, v131
	v_cvt_pk_bf16_f32 v155, v132, v133
	v_cvt_pk_bf16_f32 v156, v134, v135
	v_cvt_pk_bf16_f32 v157, v136, v137
	global_store_dwordx4 v[160:161], v[154:157], off offset:256
	s_waitcnt vmcnt(8)
	v_cvt_f32_ubyte0_e32 v130, v248
	v_cvt_f32_ubyte1_e32 v131, v248
	v_cvt_f32_ubyte2_e32 v132, v248
	v_cvt_f32_ubyte3_e32 v133, v248
	v_cvt_f32_ubyte0_e32 v134, v249
	v_cvt_f32_ubyte1_e32 v135, v249
	v_cvt_f32_ubyte2_e32 v136, v249
	v_cvt_f32_ubyte3_e32 v137, v249
	v_lshlrev_b32_e32 v138, 16, v196
	v_and_b32_e32 v139, 0xffff0000, v196
	v_lshlrev_b32_e32 v140, 16, v197
	v_and_b32_e32 v141, 0xffff0000, v197
	v_lshlrev_b32_e32 v142, 16, v198
	v_and_b32_e32 v143, 0xffff0000, v198
	v_lshlrev_b32_e32 v144, 16, v199
	v_and_b32_e32 v145, 0xffff0000, v199
	v_pk_mul_f32 v[130:131], v[130:131], s[34:35] op_sel_hi:[1,0]
	v_pk_mul_f32 v[132:133], v[132:133], s[34:35] op_sel_hi:[1,0]
	v_pk_mul_f32 v[134:135], v[134:135], s[34:35] op_sel_hi:[1,0]
	v_pk_mul_f32 v[136:137], v[136:137], s[34:35] op_sel_hi:[1,0]
	v_pk_fma_f32 v[130:131], v[12:13], v[130:131], v[138:139]
	v_pk_fma_f32 v[132:133], v[14:15], v[132:133], v[140:141]
	v_pk_fma_f32 v[134:135], v[8:9], v[134:135], v[142:143]
	v_pk_fma_f32 v[136:137], v[10:11], v[136:137], v[144:145]
	v_cvt_pk_bf16_f32 v150, v130, v131
	v_cvt_pk_bf16_f32 v151, v132, v133
	v_cvt_pk_bf16_f32 v152, v134, v135
	v_cvt_pk_bf16_f32 v153, v136, v137
	global_store_dwordx4 v[162:163], v[150:153], off
	s_waitcnt vmcnt(7)
	v_cvt_f32_ubyte0_e32 v130, v250
	v_cvt_f32_ubyte1_e32 v131, v250
	v_cvt_f32_ubyte2_e32 v132, v250
	v_cvt_f32_ubyte3_e32 v133, v250
	v_cvt_f32_ubyte0_e32 v134, v251
	v_cvt_f32_ubyte1_e32 v135, v251
	v_cvt_f32_ubyte2_e32 v136, v251
	v_cvt_f32_ubyte3_e32 v137, v251
	v_lshlrev_b32_e32 v138, 16, v200
	v_and_b32_e32 v139, 0xffff0000, v200
	v_lshlrev_b32_e32 v140, 16, v201
	v_and_b32_e32 v141, 0xffff0000, v201
	v_lshlrev_b32_e32 v142, 16, v202
	v_and_b32_e32 v143, 0xffff0000, v202
	v_lshlrev_b32_e32 v144, 16, v203
	v_and_b32_e32 v145, 0xffff0000, v203
	v_pk_mul_f32 v[130:131], v[130:131], s[34:35] op_sel_hi:[1,0]
	v_pk_mul_f32 v[132:133], v[132:133], s[34:35] op_sel_hi:[1,0]
	v_pk_mul_f32 v[134:135], v[134:135], s[34:35] op_sel_hi:[1,0]
	v_pk_mul_f32 v[136:137], v[136:137], s[34:35] op_sel_hi:[1,0]
	v_pk_fma_f32 v[130:131], v[4:5], v[130:131], v[138:139]
	v_pk_fma_f32 v[132:133], v[6:7], v[132:133], v[140:141]
	v_pk_fma_f32 v[134:135], v[0:1], v[134:135], v[142:143]
	v_pk_fma_f32 v[136:137], v[2:3], v[136:137], v[144:145]
	v_cvt_pk_bf16_f32 v154, v130, v131
	v_cvt_pk_bf16_f32 v155, v132, v133
	v_cvt_pk_bf16_f32 v156, v134, v135
	v_cvt_pk_bf16_f32 v157, v136, v137
	global_store_dwordx4 v[162:163], v[154:157], off offset:256
	s_cbranch_execnz .LBB0_202

	.amdhsa_kernel _Z6mk_fwd6Params
		.amdhsa_group_segment_fixed_size 0
		.amdhsa_private_segment_fixed_size 0
		.amdhsa_kernarg_size 448
		.amdhsa_user_sgpr_count 2
		.amdhsa_user_sgpr_dispatch_ptr 0
		.amdhsa_user_sgpr_queue_ptr 0
		.amdhsa_user_sgpr_kernarg_segment_ptr 1
		.amdhsa_user_sgpr_dispatch_id 0
		.amdhsa_user_sgpr_kernarg_preload_length 0
		.amdhsa_user_sgpr_kernarg_preload_offset 0
		.amdhsa_user_sgpr_private_segment_size 0
		.amdhsa_uses_dynamic_stack 0
		.amdhsa_enable_private_segment 0
		.amdhsa_system_sgpr_workgroup_id_x 1
		.amdhsa_system_sgpr_workgroup_id_y 0
		.amdhsa_system_sgpr_workgroup_id_z 0
		.amdhsa_system_sgpr_workgroup_info 0
		.amdhsa_system_vgpr_workitem_id 2
		.amdhsa_next_free_vgpr 256
		.amdhsa_next_free_sgpr 102
		.amdhsa_accum_offset 256
		.amdhsa_reserve_vcc 1
		.amdhsa_float_round_mode_32 0
		.amdhsa_float_round_mode_16_64 0
		.amdhsa_float_denorm_mode_32 3
		.amdhsa_float_denorm_mode_16_64 3
		.amdhsa_dx10_clamp 1
		.amdhsa_ieee_mode 1
		.amdhsa_fp16_overflow 0
		.amdhsa_tg_split 0
		.amdhsa_exception_fp_ieee_invalid_op 0
		.amdhsa_exception_fp_denorm_src 0
		.amdhsa_exception_fp_ieee_div_zero 0
		.amdhsa_exception_fp_ieee_overflow 0
		.amdhsa_exception_fp_ieee_underflow 0
		.amdhsa_exception_fp_ieee_inexact 0
		.amdhsa_exception_int_div_zero 0
	.end_amdhsa_kernel

amdhsa.kernels:
  - .agpr_count:     0
    .args:
      - .offset:         0
        .size:           192
        .value_kind:     by_value
      - .offset:         192
        .size:           4
        .value_kind:     hidden_block_count_x
      - .offset:         196
        .size:           4
        .value_kind:     hidden_block_count_y
      - .offset:         200
        .size:           4
        .value_kind:     hidden_block_count_z
      - .offset:         204
        .size:           2
        .value_kind:     hidden_group_size_x
      - .offset:         206
        .size:           2
        .value_kind:     hidden_group_size_y
      - .offset:         208
        .size:           2
        .value_kind:     hidden_group_size_z
      - .offset:         210
        .size:           2
        .value_kind:     hidden_remainder_x
      - .offset:         212
        .size:           2
        .value_kind:     hidden_remainder_y
      - .offset:         214
        .size:           2
        .value_kind:     hidden_remainder_z
      - .offset:         232
        .size:           8
        .value_kind:     hidden_global_offset_x
      - .offset:         240
        .size:           8
        .value_kind:     hidden_global_offset_y
      - .offset:         248
        .size:           8
        .value_kind:     hidden_global_offset_z
      - .offset:         256
        .size:           2
        .value_kind:     hidden_grid_dims
      - .offset:         280
        .size:           8
        .value_kind:     hidden_multigrid_sync_arg
      - .offset:         312
        .size:           4
        .value_kind:     hidden_dynamic_lds_size
    .group_segment_fixed_size: 0
    .kernarg_segment_align: 8
    .kernarg_segment_size: 448
    .language:       OpenCL C
    .language_version:
      - 2
      - 0
    .max_flat_workgroup_size: 512
    .name:           _Z6mk_fwd6Params
    .private_segment_fixed_size: 0
    .sgpr_count:     108
    .sgpr_spill_count: 67
    .symbol:         _Z6mk_fwd6Params.kd
    .uniform_work_group_size: 1
    .uses_dynamic_stack: false
    .vgpr_count:     256
    .vgpr_spill_count: 0
    .wavefront_size: 64
